# in-proj GEMM: second-group tiles swapped between workgroup halves so every workgroup gets the same mix of epilogue types
# baseline (speedup 1.0000x reference)
.Lp2_noarr:
	s_lshl_b32 s99, s79, 2
	s_lshr_b32 s99, 0x76524310, s99
	s_and_b32 s99, s99, 15
	s_mul_i32 s4, s99, s82
	s_mul_hi_u32 s5, s99, s3
	s_add_i32 s5, s5, s4
	s_cmp_gt_u32 s99, 2
	s_cselect_b32 s98, 0x80, 0
	s_xor_b32 s98, s2, s98
	s_mul_i32 s4, s99, s3
	s_add_u32 s34, s4, s98
	s_addc_u32 s35, s5, s83
	v_cmp_gt_i64_e32 vcc, s[34:35], v[146:147]
	v_cmp_lt_i64_e64 s[4:5], s[34:35], v[144:145]
	s_cbranch_vccnz .LBB0_136
	s_ashr_i32 s28, s34, 31
	s_lshr_b32 s28, s28, 29
	s_add_i32 s28, s34, s28
	s_ashr_i32 s29, s28, 3
	s_and_b32 s28, s28, -8
	s_sub_i32 s28, s34, s28
	s_cmp_lt_i32 s28, 0
	s_movk_i32 s30, 0xc1
	s_cselect_b32 s30, s30, 0xc0
	s_mul_i32 s28, s28, s30
	s_add_i32 s28, s28, s29
	s_mul_hi_i32 s29, s28, 0x2aaaaaab
	s_lshr_b32 s30, s29, 31
	s_ashr_i32 s29, s29, 4
	s_add_i32 s29, s29, s30
	s_lshl_b32 s30, s29, 2
	s_sub_i32 s31, 64, s30
	s_min_i32 s31, s31, 4
	s_abs_i32 s34, s31
	v_cvt_f32_u32_e32 v2, s34
	s_sub_i32 s36, 0, s34
	s_mulk_i32 s29, 0x60
	s_sub_i32 s29, s28, s29
	v_rcp_iflag_f32_e32 v2, v2
	s_abs_i32 s28, s29
	s_xor_b32 s35, s29, s31
	s_ashr_i32 s35, s35, 31
	v_mul_f32_e32 v2, 0x4f7ffffe, v2
	v_cvt_u32_f32_e32 v2, v2
	s_nop 0
	v_readfirstlane_b32 s37, v2
	s_mul_i32 s36, s36, s37
	s_mul_hi_u32 s36, s37, s36
	s_add_i32 s37, s37, s36
	s_mul_hi_u32 s36, s28, s37
	s_mul_i32 s37, s36, s34
	s_sub_i32 s28, s28, s37
	s_add_i32 s39, s36, 1
	s_sub_i32 s37, s28, s34
	s_cmp_ge_u32 s28, s34
	s_cselect_b32 s36, s39, s36
	s_cselect_b32 s28, s37, s28
	s_add_i32 s37, s36, 1
	s_cmp_ge_u32 s28, s34
	s_cselect_b32 s28, s37, s36
	s_xor_b32 s28, s28, s35
	s_sub_i32 s28, s28, s35
	s_mul_i32 s31, s28, s31
	s_sub_i32 s29, s29, s31
	s_add_i32 s30, s30, s29
